# w_out fp32-to-bf16 conversion item (runs in the w_in GEMM tail): 8 weight rows loaded together (was two loads per wait), on top of v048
# baseline (speedup 1.0000x reference)
; DI u16 bf1(float x) { return (u16)(pk2(x, 0.f) & 0xffffu); }
; DI void conv_tile(unsigned char* smem, const int wv, const float* __restrict__ src, u16* __restrict__ dst, int K, int N, int kind, const float* __restrict__ gain, int ktile, int ntile, bool kperm = false) {
;     ...
;   for (int i = 0; i < 8; ++i) {
;     const int k = kq * 8 + i;
;     float v = 0.f;
;     if (n < N) { v = src[(size_t)(k0 + k) * N + n]; if (gain) v *= gain[k0 + k]; }
;     T[nl][k] = bf1(v);
;   }
;   __syncthreads();
;   const int row = tid >> 3, seg = tid & 7;
;   const int nn = ntile * 64 + row;
;   if (nn < N) {
;     const int dr = perm_col(kind, nn);
;     uint4 v0;
;     if (kperm) {
;       const int base = (seg >> 2) * 32 + (seg & 1) * 16 + ((seg >> 1) & 1) * 4;
;       const uint2 lo = *(const uint2*)&T[row][base], hi = *(const uint2*)&T[row][base + 8];
;       v0 = make_uint4(lo.x, lo.y, hi.x, hi.y);
;     } else {
;       v0 = *(const uint4*)&T[row][seg * 8];
;     }
;     *(uint4*)(dst + (size_t)dr * K + k0 + seg * 8) = v0;
.LBB0_951:
	s_andn2_b64 vcc, exec, s[2:3]
	s_cbranch_vccnz .LBB0_955
	s_add_i32 s2, s19, 0xfffffdb8
	v_mbcnt_lo_u32_b32 v1, -1, 0
	v_mbcnt_hi_u32_b32 v1, -1, v1
	s_lshl_b32 s3, s2, 2
	v_add_u32_e32 v0, s29, v1
	v_ashrrev_i32_e32 v2, 3, v0
	s_lshl_b32 s2, s2, 6
	s_and_b32 s26, s3, 0x7fffffc0
	v_and_b32_e32 v0, -8, v2
	v_and_b32_e32 v3, 63, v1
	s_and_b32 s2, s2, 0x3c0
	v_or_b32_e32 v100, s2, v3
	v_add_u32_e32 v102, s26, v0
	v_lshlrev_b32_e32 v164, 2, v100
	v_or_b32_e32 v166, 1, v102
	v_ashrrev_i32_e32 v103, 31, v102
	v_lshl_add_u64 v[100:101], s[66:67], 0, v[164:165]
	v_ashrrev_i32_e32 v167, 31, v166
	v_lshlrev_b64 v[102:103], 12, v[102:103]
	v_lshlrev_b64 v[166:167], 12, v[166:167]
	v_lshl_add_u64 v[102:103], v[100:101], 0, v[102:103]
	s_barrier
	v_lshl_add_u64 v[166:167], v[100:101], 0, v[166:167]
	s_mov_b64 s[36:37], 0x2000
	v_lshl_add_u64 v[206:207], v[166:167], 0, s[36:37]
	v_lshl_add_u64 v[208:209], v[206:207], 0, s[36:37]
	v_lshl_add_u64 v[224:225], v[208:209], 0, s[36:37]
	global_load_dword v212, v[166:167], off offset:-4096
	global_load_dword v213, v[166:167], off
	global_load_dword v214, v[206:207], off offset:-4096
	global_load_dword v215, v[206:207], off
	global_load_dword v216, v[208:209], off offset:-4096
	global_load_dword v217, v[208:209], off
	global_load_dword v218, v[224:225], off offset:-4096
	global_load_dword v219, v[224:225], off
	s_movk_i32 s0, 0x90
	v_lshlrev_b32_e32 v103, 1, v0
	v_mad_u32_u24 v103, v3, s0, v103
	s_waitcnt vmcnt(0)
	v_cvt_pk_bf16_f32 v220, v212, v213
	v_cvt_pk_bf16_f32 v221, v214, v215
	v_cvt_pk_bf16_f32 v222, v216, v217
	v_cvt_pk_bf16_f32 v223, v218, v219
	ds_write_b32 v103, v220
	ds_write_b32 v103, v221 offset:4
	ds_write_b32 v103, v222 offset:8
	ds_write_b32 v103, v223 offset:12
	s_movk_i32 s0, 0x400
	v_add_u32_e32 v0, s2, v2
	v_cmp_gt_i32_e32 vcc, s0, v0
	s_waitcnt lgkmcnt(0)
	s_barrier
	s_and_saveexec_b64 s[2:3], vcc
	s_cbranch_execz .LBB0_954
	s_movk_i32 s0, 0x90
	v_lshlrev_b32_e32 v3, 4, v1
	v_mul_lo_u32 v2, v2, s0
	v_lshlrev_b32_e32 v100, 2, v1
	v_lshlrev_b32_e32 v1, 5, v1
	v_and_or_b32 v2, v100, 8, v2
	v_and_b32_e32 v1, 32, v1
	v_and_b32_e32 v100, 64, v3
	v_add3_u32 v2, v2, v1, v100
	v_ashrrev_i32_e32 v1, 31, v0
	v_readlane_b32 s36, v250, 55
	v_lshlrev_b64 v[0:1], 11, v[0:1]
	v_readlane_b32 s37, v250, 56
	s_mov_b32 s27, s43
	s_lshl_b32 s26, s26, 1
	v_lshl_add_u64 v[0:1], s[36:37], 0, v[0:1]
	v_lshl_add_u64 v[0:1], v[0:1], 0, s[26:27]
	v_and_b32_e32 v164, 0x70, v3
	v_lshl_add_u64 v[100:101], v[0:1], 0, v[164:165]
	ds_read2_b64 v[0:3], v2 offset1:2
	s_waitcnt lgkmcnt(0)
	global_store_dwordx4 v[100:101], v[0:3], off
